# mixer phase: gMLP after the first attention unit for every workgroup, attention-only passes skip the gMLP preamble (LayerNorm gain/bias staging)
# speedup vs baseline: 1.0079x; 1.0009x over previous
.LBB0_122:
	s_or_b64 exec, exec, s[2:3]
	v_readlane_b32 s0, v255, 61
	s_nop 3
	s_bitcmp1_b32 s0, 0
	s_cbranch_scc0 .Lgd_pre
	v_and_b32_e32 v157, 31, v200
	s_branch .LBB0_126
.Lgd_pre:
	global_load_dwordx4 v[6:9], v[2:3], off
	v_readlane_b32 s0, v251, 18
	v_lshl_add_u32 v0, v0, 2, 0
	s_add_i32 s16, s83, s0
	v_and_b32_e32 v157, 31, v200
	v_add_u32_e32 v0, 0x22000, v0
	s_cmpk_gt_i32 s16, 0x7ff
	s_waitcnt vmcnt(0)
	ds_write_b128 v0, v[6:9]
	s_waitcnt lgkmcnt(0)
	s_barrier
	s_cbranch_scc1 .LBB0_126
	v_readlane_b32 s0, v255, 61
	s_nop 3
	s_bitcmp1_b32 s0, 0
	s_cbranch_scc1 .LBB0_126
	v_readlane_b32 s0, v252, 27
	v_lshrrev_b32_e32 v0, 5, v244
	v_readlane_b32 s0, v251, 23
	v_lshlrev_b32_e32 v1, 3, v0
	s_lshl_b64 s[0:1], s[94:95], 18
	v_readlane_b32 s2, v251, 21
	v_or_b32_e32 v3, 7, v1
	v_readlane_b32 s3, v251, 22
	s_add_u32 s0, s2, s0
	v_cmp_gt_u32_e64 s[84:85], v3, v157
	v_or_b32_e32 v3, 6, v1
	s_addc_u32 s1, s3, s1
	v_lshlrev_b32_e32 v192, 4, v0
	v_cmp_gt_u32_e64 s[86:87], v3, v157
	v_or_b32_e32 v3, 5, v1
	v_lshl_add_u64 v[158:159], s[0:1], 0, v[192:193]
	v_cmp_gt_u32_e64 s[0:1], v3, v157
	v_or_b32_e32 v3, 4, v1
	v_or_b32_e32 v2, 32, v244
	v_writelane_b32 v253, s0, 53
	v_readlane_b32 s4, v251, 4
	s_lshl_b64 s[2:3], s[94:95], 12
	v_writelane_b32 v253, s1, 54
	v_cmp_gt_u32_e64 s[0:1], v3, v157
	v_or_b32_e32 v3, 3, v1
	v_readlane_b32 s6, v251, 6
	v_writelane_b32 v253, s0, 55
	v_readlane_b32 s7, v251, 7
	s_add_u32 s12, s6, s2
	v_writelane_b32 v253, s1, 56
	v_cmp_gt_u32_e64 s[0:1], v3, v157
	v_or_b32_e32 v3, 2, v1
	s_mul_i32 s2, s83, 0x4400
	v_writelane_b32 v253, s0, 57
	s_addc_u32 s13, s7, s3
	s_add_i32 s2, s2, 0
	v_writelane_b32 v253, s1, 58
	v_cmp_gt_u32_e64 s[0:1], v3, v157
	v_or_b32_e32 v3, 23, v1
	v_add_u32_e32 v161, s2, v4
	v_writelane_b32 v253, s0, 59
	v_or_b32_e32 v4, 0x47, v1
	v_lshl_add_u32 v165, v0, 6, s2
	v_writelane_b32 v253, s1, 60
	v_cmp_lt_u32_e64 s[0:1], v1, v157
	v_and_b32_e32 v0, 7, v200
	v_add_u32_e32 v163, s2, v192
	v_writelane_b32 v253, s0, 61
	v_lshlrev_b32_e32 v167, 3, v0
	v_lshl_add_u32 v0, v0, 5, s2
	v_writelane_b32 v253, s1, 62
	v_cmp_gt_u32_e64 s[0:1], v3, v157
	v_or_b32_e32 v3, 22, v1
	s_lshl_b32 s14, s83, 6
	v_writelane_b32 v253, s0, 63
	v_readlane_b32 s5, v251, 5
	v_lshrrev_b32_e32 v160, 3, v244
	v_writelane_b32 v254, s1, 0
	v_cmp_gt_u32_e64 s[0:1], v3, v157
	v_or_b32_e32 v3, 21, v1
	v_readlane_b32 s8, v251, 8
	v_writelane_b32 v254, s0, 1
	v_readlane_b32 s9, v251, 9
	v_readlane_b32 s10, v251, 10
	v_writelane_b32 v254, s1, 2
	v_cmp_gt_u32_e64 s[0:1], v3, v157
	v_or_b32_e32 v3, 20, v1
	v_readlane_b32 s11, v251, 11
	v_writelane_b32 v254, s0, 3
	v_mul_u32_u24_e32 v171, 0x110, v2
	v_cmp_gt_u32_e64 s[52:53], v1, v157
	v_writelane_b32 v254, s1, 4
	v_cmp_gt_u32_e64 s[0:1], v3, v157
	v_or_b32_e32 v3, 19, v1
	v_readlane_b32 s36, v252, 13
	v_writelane_b32 v254, s0, 5
	v_readlane_b32 s80, v252, 17
	v_readlane_b32 s28, v252, 15
	v_writelane_b32 v254, s1, 6
	v_cmp_gt_u32_e64 s[0:1], v3, v157
	v_or_b32_e32 v3, 18, v1
	v_readlane_b32 s4, v252, 19
	v_writelane_b32 v254, s0, 7
	s_mov_b32 s27, s46
	v_lshlrev_b32_e32 v156, 1, v244
	v_writelane_b32 v254, s1, 8
	v_cmp_gt_u32_e64 s[0:1], v3, v157
	v_or_b32_e32 v3, 17, v1
	v_or_b32_e32 v162, 64, v160
	v_writelane_b32 v254, s0, 9
	v_mul_u32_u24_e32 v169, 0x110, v157
	v_or_b32_e32 v164, 8, v160
	v_writelane_b32 v254, s1, 10
	v_cmp_gt_u32_e64 s[0:1], v3, v157
	v_or_b32_e32 v3, 16, v1
	v_or_b32_e32 v166, 16, v160
	v_writelane_b32 v254, s0, 11
	v_or_b32_e32 v168, 24, v160
	v_or_b32_e32 v170, 32, v160
	v_writelane_b32 v254, s1, 12
	v_cmp_gt_u32_e64 s[0:1], v3, v157
	v_or_b32_e32 v3, 39, v1
	v_or_b32_e32 v172, 40, v160
	v_writelane_b32 v254, s0, 13
	v_or_b32_e32 v174, 48, v160
	v_or_b32_e32 v176, 56, v160
	v_writelane_b32 v254, s1, 14
	v_cmp_gt_u32_e64 s[0:1], v3, v2
	v_or_b32_e32 v3, 38, v1
	v_or_b32_e32 v178, 0x48, v160
	v_writelane_b32 v254, s0, 15
	v_or_b32_e32 v180, 0x50, v160
	v_or_b32_e32 v182, 0x58, v160
	v_writelane_b32 v254, s1, 16
	v_cmp_gt_u32_e64 s[0:1], v3, v2
	v_or_b32_e32 v3, 37, v1
	v_or_b32_e32 v184, 0x60, v160
	v_writelane_b32 v254, s0, 17
	v_or_b32_e32 v186, 0x68, v160
	v_or_b32_e32 v188, 0x70, v160
	v_writelane_b32 v254, s1, 18
	v_cmp_gt_u32_e64 s[0:1], v3, v2
	v_or_b32_e32 v3, 36, v1
	v_or_b32_e32 v190, 0x78, v160
	v_writelane_b32 v254, s0, 19
	v_readlane_b32 s37, v252, 14
	v_readlane_b32 s81, v252, 18
	v_writelane_b32 v254, s1, 20
	v_cmp_gt_u32_e64 s[0:1], v3, v2
	v_or_b32_e32 v3, 35, v1
	v_readlane_b32 s29, v252, 16
	v_writelane_b32 v254, s0, 21
	v_readlane_b32 s5, v252, 20
	v_readlane_b32 s23, v253, 12
	v_writelane_b32 v254, s1, 22
	v_cmp_gt_u32_e64 s[0:1], v3, v2
	v_or_b32_e32 v3, 34, v1
	s_movk_i32 s25, 0x4000
	v_writelane_b32 v254, s0, 23
	s_mov_b32 s44, 0x3a800000
	s_nop 0
	v_writelane_b32 v254, s1, 24
	v_cmp_gt_u32_e64 s[0:1], v3, v2
	v_or_b32_e32 v3, 33, v1
	s_nop 0
	v_writelane_b32 v254, s0, 25
	s_nop 1
	v_writelane_b32 v254, s1, 26
	v_cmp_gt_u32_e64 s[0:1], v3, v2
	v_or_b32_e32 v3, 32, v1
	s_nop 0
	v_writelane_b32 v254, s0, 27
	s_nop 1
	v_writelane_b32 v254, s1, 28
	v_cmp_gt_u32_e64 s[0:1], v3, v2
	v_or_b32_e32 v3, 55, v1
	s_nop 0
	v_writelane_b32 v254, s0, 29
	s_nop 1
	v_writelane_b32 v254, s1, 30
	v_cmp_gt_u32_e64 s[0:1], v3, v2
	v_or_b32_e32 v3, 54, v1
	s_nop 0
	v_writelane_b32 v254, s0, 31
	s_nop 1
	v_writelane_b32 v254, s1, 32
	v_cmp_gt_u32_e64 s[0:1], v3, v2
	v_or_b32_e32 v3, 53, v1
	s_nop 0
	v_writelane_b32 v254, s0, 33
	s_nop 1
	v_writelane_b32 v254, s1, 34
	v_cmp_gt_u32_e64 s[0:1], v3, v2
	v_or_b32_e32 v3, 52, v1
	s_nop 0
	v_writelane_b32 v254, s0, 35
	s_nop 1
	v_writelane_b32 v254, s1, 36
	v_cmp_gt_u32_e64 s[0:1], v3, v2
	v_or_b32_e32 v3, 51, v1
	s_nop 0
	v_writelane_b32 v254, s0, 37
	s_nop 1
	v_writelane_b32 v254, s1, 38
	v_cmp_gt_u32_e64 s[0:1], v3, v2
	v_or_b32_e32 v3, 50, v1
	s_nop 0
	v_writelane_b32 v254, s0, 39
	s_nop 1
	v_writelane_b32 v254, s1, 40
	v_cmp_gt_u32_e64 s[0:1], v3, v2
	v_or_b32_e32 v3, 49, v1
	s_nop 0
	v_writelane_b32 v254, s0, 41
	s_nop 1
	v_writelane_b32 v254, s1, 42
	v_cmp_gt_u32_e64 s[0:1], v3, v2
	v_or_b32_e32 v3, 48, v1
	s_nop 0
	v_writelane_b32 v254, s0, 43
	s_nop 1
	v_writelane_b32 v254, s1, 44
	v_cmp_gt_u32_e64 s[0:1], v3, v2
	v_or_b32_e32 v3, 64, v157
	v_mul_u32_u24_e32 v2, 0x110, v160
	v_writelane_b32 v254, s0, 45
	v_add_u32_e32 v173, v0, v2
	s_nop 0
	v_writelane_b32 v254, s1, 46
	v_cmp_gt_u32_e64 s[0:1], v4, v3
	v_or_b32_e32 v4, 0x46, v1
	s_nop 0
	v_writelane_b32 v254, s0, 47
	s_nop 1
	v_writelane_b32 v254, s1, 48
	v_cmp_gt_u32_e64 s[0:1], v4, v3
	v_or_b32_e32 v4, 0x45, v1
	s_nop 0
	v_writelane_b32 v254, s0, 49
	s_nop 1
	v_writelane_b32 v254, s1, 50
	v_cmp_gt_u32_e64 s[0:1], v4, v3
	v_or_b32_e32 v4, 0x44, v1
	s_nop 0
	v_writelane_b32 v254, s0, 51
	s_nop 1
	v_writelane_b32 v254, s1, 52
	v_cmp_gt_u32_e64 s[0:1], v4, v3
	v_or_b32_e32 v4, 0x43, v1
	s_nop 0
	v_writelane_b32 v254, s0, 53
	s_nop 1
	v_writelane_b32 v254, s1, 54
	v_cmp_gt_u32_e64 s[0:1], v4, v3
	v_or_b32_e32 v4, 0x42, v1
	s_nop 0
	v_writelane_b32 v254, s0, 55
	s_nop 1
	v_writelane_b32 v254, s1, 56
	v_cmp_gt_u32_e64 s[0:1], v4, v3
	v_or_b32_e32 v4, 0x41, v1
	s_nop 0
	v_writelane_b32 v254, s0, 57
	s_nop 1
	v_writelane_b32 v254, s1, 58
	v_cmp_gt_u32_e64 s[0:1], v4, v3
	v_or_b32_e32 v4, 0x57, v1
	s_nop 0
	v_writelane_b32 v254, s0, 59
	s_nop 1
	v_writelane_b32 v254, s1, 60
	v_cmp_gt_u32_e64 s[0:1], v4, v3
	v_or_b32_e32 v4, 0x56, v1
	s_nop 0
	v_writelane_b32 v254, s0, 61
	s_nop 1
	v_writelane_b32 v254, s1, 62
	v_cmp_gt_u32_e64 s[0:1], v4, v3
	v_or_b32_e32 v4, 0x55, v1
	s_nop 0
	v_writelane_b32 v254, s0, 63
	s_nop 1
	v_writelane_b32 v255, s1, 0
	v_cmp_gt_u32_e64 s[0:1], v4, v3
	v_or_b32_e32 v4, 0x54, v1
	s_nop 0
	v_writelane_b32 v255, s0, 1
	s_nop 1
	v_writelane_b32 v255, s1, 2
	v_cmp_gt_u32_e64 s[0:1], v4, v3
	v_or_b32_e32 v4, 0x53, v1
	s_nop 0
	v_writelane_b32 v255, s0, 3
	s_nop 1
	v_writelane_b32 v255, s1, 4
	v_cmp_gt_u32_e64 s[0:1], v4, v3
	v_or_b32_e32 v4, 0x52, v1
	s_nop 0
	v_writelane_b32 v255, s0, 5
	s_nop 1
	v_writelane_b32 v255, s1, 6
	v_cmp_gt_u32_e64 s[0:1], v4, v3
	v_or_b32_e32 v4, 0x51, v1
	s_nop 0
	v_writelane_b32 v255, s0, 7
	s_nop 1
	v_writelane_b32 v255, s1, 8
	v_cmp_gt_u32_e64 s[0:1], v4, v3
	v_or_b32_e32 v4, 0x50, v1
	s_nop 0
	v_writelane_b32 v255, s0, 9
	s_nop 1
	v_writelane_b32 v255, s1, 10
	v_cmp_gt_u32_e64 s[0:1], v4, v3
	v_or_b32_e32 v3, 0x60, v244
	v_or_b32_e32 v4, 0x67, v1
	v_writelane_b32 v255, s0, 11
	s_nop 1
	v_writelane_b32 v255, s1, 12
	v_cmp_gt_u32_e64 s[0:1], v4, v3
	v_or_b32_e32 v4, 0x66, v1
	s_nop 0
	v_writelane_b32 v255, s0, 13
	s_nop 1
	v_writelane_b32 v255, s1, 14
	v_cmp_gt_u32_e64 s[0:1], v4, v3
	v_or_b32_e32 v4, 0x65, v1
	s_nop 0
	v_writelane_b32 v255, s0, 15
	s_nop 1
	v_writelane_b32 v255, s1, 16
	v_cmp_gt_u32_e64 s[0:1], v4, v3
	v_or_b32_e32 v4, 0x64, v1
	s_nop 0
	v_writelane_b32 v255, s0, 17
	s_nop 1
	v_writelane_b32 v255, s1, 18
	v_cmp_gt_u32_e64 s[0:1], v4, v3
	v_or_b32_e32 v4, 0x63, v1
	s_nop 0
	v_writelane_b32 v255, s0, 19
	s_nop 1
	v_writelane_b32 v255, s1, 20
	v_cmp_gt_u32_e64 s[0:1], v4, v3
	v_or_b32_e32 v4, 0x62, v1
	s_nop 0
	v_writelane_b32 v255, s0, 21
	s_nop 1
	v_writelane_b32 v255, s1, 22
	v_cmp_gt_u32_e64 s[0:1], v4, v3
	v_or_b32_e32 v4, 0x61, v1
	s_nop 0
	v_writelane_b32 v255, s0, 23
	s_nop 1
	v_writelane_b32 v255, s1, 24
	v_cmp_gt_u32_e64 s[0:1], v4, v3
	v_or_b32_e32 v4, 0x60, v1
	s_nop 0
	v_writelane_b32 v255, s0, 25
	s_nop 1
	v_writelane_b32 v255, s1, 26
	v_cmp_gt_u32_e64 s[0:1], v4, v3
	v_or_b32_e32 v4, 0x77, v1
	s_nop 0
	v_writelane_b32 v255, s0, 27
	s_nop 1
	v_writelane_b32 v255, s1, 28
	v_cmp_gt_u32_e64 s[0:1], v4, v3
	v_or_b32_e32 v4, 0x76, v1
	s_nop 0
	v_writelane_b32 v255, s0, 29
	s_nop 1
	v_writelane_b32 v255, s1, 30
	v_cmp_gt_u32_e64 s[0:1], v4, v3
	v_or_b32_e32 v4, 0x75, v1
	s_nop 0
	v_writelane_b32 v255, s0, 31
	s_nop 1
	v_writelane_b32 v255, s1, 32
	v_cmp_gt_u32_e64 s[0:1], v4, v3
	v_or_b32_e32 v4, 0x74, v1
	v_cmp_gt_u32_e64 s[2:3], v4, v3
	v_writelane_b32 v255, s0, 33
	v_or_b32_e32 v4, 0x73, v1
	v_cmp_gt_u32_e64 s[40:41], v4, v3
	v_writelane_b32 v255, s1, 34
	v_readlane_b32 s0, v253, 10
	v_or_b32_e32 v4, 0x72, v1
	s_add_i32 s17, s0, s14
	s_lshl_b32 s14, s83, 3
	v_readlane_b32 s0, v253, 11
	v_cmp_gt_u32_e64 s[6:7], v4, v3
	v_or_b32_e32 v4, 0x71, v1
	v_or_b32_e32 v1, 0x70, v1
	s_add_i32 s18, s0, s14
	v_readlane_b32 s14, v253, 39
	v_readlane_b32 s0, v252, 21
	v_cmp_gt_u32_e64 s[8:9], v4, v3
	v_cmp_gt_u32_e64 s[10:11], v1, v3
	s_mov_b32 s26, s14
	v_readlane_b32 s1, v252, 22
	v_readlane_b32 s15, v253, 40
